# attention softmax block: tile-uniform mask via scalar branch instead of 16 v_cndmask, max tree with v_max3 and no canonicalising maxes (-30 VALU per wave per step)
# baseline (speedup 1.0000x reference)
; template <int KB> __device__ __forceinline__ void qkt_half(f32x16& p, const char* K_lds, int r32, int hi, int kh, const char* qf, bf16x8 q0) {
;     p = f32x16{};
;     const char* kb[4];
; #pragma unroll
;     for (int dd = 0; dd < 4; ++dd) kb[dd] = K_lds + KB * SHM_K + kh * 8192 + KSWZ(r32, (dd * 16 + hi * 8) * 2);
; #pragma unroll
;     for (int d0 = 0; d0 < 8; ++d0) { const bf16x8 b0 = *reinterpret_cast<const bf16x8*>(kb[d0 & 3] + (d0 >> 2) * 128); const bf16x8 q = d0 == 0 ? q0 : *reinterpret_cast<const bf16x8*>(qf + (d0 - 1) * 1024); p = __builtin_amdgcn_mfma_f32_32x32x16_bf16(b0, q, p, 0, 0, 0); }
.LBB0_369:
	ds_read_b128 v[184:187], v220 offset:16384
	ds_read_b128 v[180:183], v220 offset:17408
	ds_read_b128 v[64:67], v211
	ds_read_b128 v[68:71], v211 offset:128
	s_waitcnt lgkmcnt(1)
	v_mfma_f32_32x32x16_bf16 v[128:143], v[64:67], v[144:147], 0
	ds_read_b128 v[64:67], v212
	ds_read_b128 v[72:75], v210
	ds_read_b128 v[76:79], v210 offset:1024
	ds_read_b128 v[80:83], v212 offset:128
	s_waitcnt lgkmcnt(2)
	v_mfma_f32_32x32x16_bf16 v[128:143], v[64:67], v[72:75], v[128:143]
	ds_read_b128 v[64:67], v213
	ds_read_b128 v[72:75], v213 offset:128
	s_waitcnt lgkmcnt(1)
	v_mfma_f32_32x32x16_bf16 v[128:143], v[64:67], v[76:79], v[128:143]
	ds_read_b128 v[64:67], v214
	ds_read_b128 v[76:79], v210 offset:2048
	ds_read_b128 v[84:87], v210 offset:3072
	ds_read_b128 v[88:91], v214 offset:128
	s_waitcnt lgkmcnt(2)
	v_mfma_f32_32x32x16_bf16 v[128:143], v[64:67], v[76:79], v[128:143]
	s_waitcnt lgkmcnt(1)
	v_mfma_f32_32x32x16_bf16 v[128:143], v[68:71], v[84:87], v[128:143]
	ds_read_b128 v[64:67], v210 offset:4096
	ds_read_b128 v[68:71], v210 offset:5120
	s_waitcnt lgkmcnt(1)
	v_mfma_f32_32x32x16_bf16 v[128:143], v[80:83], v[64:67], v[128:143]
	ds_read_b128 v[64:67], v210 offset:6144
	s_waitcnt lgkmcnt(1)
	v_mfma_f32_32x32x16_bf16 v[128:143], v[72:75], v[68:71], v[128:143]
	s_waitcnt lgkmcnt(0)
	v_mfma_f32_32x32x16_bf16 v[128:143], v[88:91], v[64:67], v[128:143]
	s_mov_b64 s[4:5], -1
	s_and_b64 vcc, exec, s[48:49]
	s_cbranch_vccz .LBB0_371
	ds_read_b64_tr_b16 v[80:81], v194 offset:0xc000
	ds_read_b64_tr_b16 v[82:83], v194 offset:0xc800
	ds_read_b64_tr_b16 v[84:85], v194 offset:0xd000
	ds_read_b64_tr_b16 v[86:87], v194 offset:0xd800
	ds_read_b64_tr_b16 v[88:89], v194 offset:0xe000
	ds_read_b64_tr_b16 v[90:91], v194 offset:0xe800
	ds_read_b64_tr_b16 v[92:93], v194 offset:0xf000
	ds_read_b64_tr_b16 v[94:95], v194 offset:0xf800
	s_waitcnt lgkmcnt(0)
	s_nop 0
	v_mfma_f32_32x32x16_bf16 v[64:79], v[184:187], v[80:83], v[0:15]
	ds_read_b64_tr_b16 v[96:97], v194 offset:0xc200
	ds_read_b64_tr_b16 v[98:99], v194 offset:0xca00
	ds_read_b64_tr_b16 v[100:101], v194 offset:0xd200
	ds_read_b64_tr_b16 v[102:103], v194 offset:0xda00
	ds_read_b64_tr_b16 v[104:105], v194 offset:0xe200
	ds_read_b64_tr_b16 v[106:107], v194 offset:0xea00
	ds_read_b64_tr_b16 v[108:109], v194 offset:0xf200
	v_mfma_f32_32x32x16_bf16 v[64:79], v[180:183], v[84:87], v[64:79]
	ds_read_b64_tr_b16 v[110:111], v194 offset:0xfa00
	v_mfma_f32_32x32x16_bf16 v[64:79], v[172:175], v[88:91], v[64:79]
	v_mfma_f32_32x32x16_bf16 v[64:79], v[176:179], v[92:95], v[64:79]
	s_waitcnt lgkmcnt(0)
	v_mfma_f32_32x32x16_bf16 v[80:95], v[184:187], v[96:99], v[16:31]
	ds_read_b64_tr_b16 v[112:113], v194 offset:0xc400
	ds_read_b64_tr_b16 v[114:115], v194 offset:0xcc00
	ds_read_b64_tr_b16 v[116:117], v194 offset:0xd400
	ds_read_b64_tr_b16 v[118:119], v194 offset:0xdc00
	ds_read_b64_tr_b16 v[120:121], v194 offset:0xe400
	ds_read_b64_tr_b16 v[122:123], v194 offset:0xec00
	ds_read_b64_tr_b16 v[124:125], v194 offset:0xf400
	v_mfma_f32_32x32x16_bf16 v[80:95], v[180:183], v[100:103], v[80:95]
	ds_read_b64_tr_b16 v[126:127], v194 offset:0xfc00
	s_add_i32 s38, s87, -3
	s_add_i32 s50, s53, 1
	s_and_b64 s[4:5], s[46:47], exec
	s_cselect_b32 s4, s38, s50
	s_lshl_b32 s4, s4, 6
	s_cmp_le_i32 s4, s86
	s_cbranch_scc1 .Lm0_h1B_nm
	v_mov_b32_e32 v128, v204
	v_mov_b32_e32 v129, v204
	v_mov_b32_e32 v130, v204
	v_mov_b32_e32 v131, v204
	v_mov_b32_e32 v132, v204
	v_mov_b32_e32 v133, v204
	v_mov_b32_e32 v134, v204
	v_mov_b32_e32 v135, v204
	v_mov_b32_e32 v136, v204
	v_mov_b32_e32 v137, v204
	v_mov_b32_e32 v138, v204
	v_mov_b32_e32 v139, v204
	v_mov_b32_e32 v140, v204
	v_mov_b32_e32 v141, v204
	v_mov_b32_e32 v142, v204
	v_mov_b32_e32 v143, v204
.Lm0_h1B_nm:
	v_max3_f32 v0, v128, v129, v130
	v_max3_f32 v17, v131, v132, v133
	v_max3_f32 v18, v134, v135, v136
	v_max3_f32 v19, v137, v138, v139
	v_mfma_f32_32x32x16_bf16 v[80:95], v[172:175], v[104:107], v[80:95]
	v_max3_f32 v20, v140, v141, v142
	v_max3_f32 v0, v0, v17, v143
	v_max3_f32 v18, v18, v19, v20
	v_max_f32_e32 v0, v0, v18
	v_mov_b32_e32 v17, v0
	s_nop 1
	v_permlane32_swap_b32_e32 v0, v17
	v_max_f32_e32 v0, v0, v17
	v_mfma_f32_32x32x16_bf16 v[80:95], v[176:179], v[108:111], v[80:95]
	s_waitcnt lgkmcnt(0)
	v_mfma_f32_32x32x16_bf16 v[96:111], v[184:187], v[112:115], v[32:47]
	ds_read_b64_tr_b16 v[230:231], v194 offset:0xc600
	ds_read_b64_tr_b16 v[232:233], v194 offset:0xce00
	ds_read_b64_tr_b16 v[234:235], v194 offset:0xd600
	ds_read_b64_tr_b16 v[236:237], v194 offset:0xde00
	ds_read_b64_tr_b16 v[238:239], v194 offset:0xe600
	ds_read_b64_tr_b16 v[240:241], v194 offset:0xee00
	ds_read_b64_tr_b16 v[242:243], v194 offset:0xf600
	s_and_saveexec_b64 s[4:5], s[2:3]
	ds_write_b32 v226, v0
	s_or_b64 exec, exec, s[4:5]
	s_cmp_le_u32 s38, s84
	s_cselect_b64 s[4:5], -1, 0
	s_cmp_gt_u32 s38, s84
	s_cbranch_scc1 .Lm0_h1B_381
	s_waitcnt vmcnt(1)
	ds_write_b128 v215, v[148:151]
	s_waitcnt vmcnt(0)
	ds_write_b128 v215, v[152:155] offset:8192

.Lm0_h1B_385:
	s_waitcnt lgkmcnt(0)
	v_mfma_f32_32x32x16_bf16 v[112:127], v[184:187], v[230:233], v[48:63]
	v_mul_f32_e32 v17, 0xbe0293ee, v218
	v_fmamk_f32 v16, v128, 0x3e0293ee, v17
	v_fmamk_f32 v15, v129, 0x3e0293ee, v17
	v_fmamk_f32 v14, v130, 0x3e0293ee, v17
	v_fmamk_f32 v13, v131, 0x3e0293ee, v17
	v_exp_f32_e32 v16, v16
	v_exp_f32_e32 v15, v15
	v_exp_f32_e32 v14, v14
	v_exp_f32_e32 v13, v13
	v_mfma_f32_32x32x16_bf16 v[112:127], v[180:183], v[234:237], v[112:127]
	v_fmamk_f32 v12, v132, 0x3e0293ee, v17
	v_fmamk_f32 v11, v133, 0x3e0293ee, v17
	v_fmamk_f32 v10, v134, 0x3e0293ee, v17
	v_fmamk_f32 v9, v135, 0x3e0293ee, v17
	v_exp_f32_e32 v12, v12
	v_exp_f32_e32 v11, v11
	v_exp_f32_e32 v10, v10
	v_exp_f32_e32 v9, v9
	v_mfma_f32_32x32x16_bf16 v[112:127], v[172:175], v[238:241], v[112:127]
	v_fmamk_f32 v8, v136, 0x3e0293ee, v17
	v_fmamk_f32 v7, v137, 0x3e0293ee, v17
	v_fmamk_f32 v6, v138, 0x3e0293ee, v17
	v_fmamk_f32 v5, v139, 0x3e0293ee, v17
	v_exp_f32_e32 v8, v8
	v_exp_f32_e32 v7, v7
	v_exp_f32_e32 v6, v6
	v_exp_f32_e32 v5, v5
	v_mfma_f32_32x32x16_bf16 v[112:127], v[176:179], v[242:245], v[112:127]
	v_fmamk_f32 v4, v140, 0x3e0293ee, v17
	v_fmamk_f32 v3, v141, 0x3e0293ee, v17
	v_fmamk_f32 v2, v142, 0x3e0293ee, v17
	v_fmac_f32_e32 v17, 0x3e0293ee, v143
	v_exp_f32_e32 v4, v4
	v_exp_f32_e32 v3, v3
	v_exp_f32_e32 v2, v2
	v_exp_f32_e32 v1, v17
	v_add_f32_e32 v17, v16, v15
	v_add_f32_e32 v18, v14, v13
	v_add_f32_e32 v17, v17, v18
	v_add_f32_e32 v18, v12, v11
	v_add_f32_e32 v19, v10, v9
	v_add_f32_e32 v18, v18, v19
	v_add_f32_e32 v17, v17, v18
	v_add_f32_e32 v18, v8, v7
	v_add_f32_e32 v19, v6, v5
	v_add_f32_e32 v18, v18, v19
	v_add_f32_e32 v19, v4, v3
	v_add_f32_e32 v20, v2, v1
	v_add_f32_e32 v19, v19, v20
	v_add_f32_e32 v18, v18, v19
	v_add_f32_e32 v231, v17, v18
	v_mov_b32_e32 v232, v231
	s_nop 1
	v_permlane32_swap_b32_e32 v231, v232
	v_cvt_pk_bf16_f32 v172, v16, v15
	v_cvt_pk_bf16_f32 v173, v14, v13
	v_cvt_pk_bf16_f32 v174, v12, v11
	v_cvt_pk_bf16_f32 v175, v10, v9
	v_cvt_pk_bf16_f32 v176, v8, v7
	v_cvt_pk_bf16_f32 v177, v6, v5
	v_cvt_pk_bf16_f32 v178, v4, v3
	v_cvt_pk_bf16_f32 v179, v2, v1
	s_nop 0
	v_permlane32_swap_b32_e32 v172, v174
	v_permlane32_swap_b32_e32 v173, v175
	v_permlane32_swap_b32_e32 v176, v178
	v_permlane32_swap_b32_e32 v177, v179
	ds_write_b128 v219, v[172:175]
	ds_write_b128 v219, v[176:179] offset:1024
	s_mov_b64 s[4:5], 0
.LBB0_371:
	s_andn2_b64 vcc, exec, s[4:5]
	s_cbranch_vccnz .LBB0_373
	ds_read_b64_tr_b16 v[80:81], v194 offset:0x8000
	ds_read_b64_tr_b16 v[82:83], v194 offset:0x8800
	ds_read_b64_tr_b16 v[84:85], v194 offset:0x9000
	ds_read_b64_tr_b16 v[86:87], v194 offset:0x9800
	ds_read_b64_tr_b16 v[88:89], v194 offset:0xa000
	ds_read_b64_tr_b16 v[90:91], v194 offset:0xa800
	ds_read_b64_tr_b16 v[92:93], v194 offset:0xb000
	ds_read_b64_tr_b16 v[94:95], v194 offset:0xb800
	s_waitcnt lgkmcnt(0)
	s_nop 0
	v_mfma_f32_32x32x16_bf16 v[64:79], v[172:175], v[80:83], v[0:15]
	ds_read_b64_tr_b16 v[96:97], v194 offset:0x8200
	ds_read_b64_tr_b16 v[98:99], v194 offset:0x8a00
	ds_read_b64_tr_b16 v[100:101], v194 offset:0x9200
	ds_read_b64_tr_b16 v[102:103], v194 offset:0x9a00
	ds_read_b64_tr_b16 v[104:105], v194 offset:0xa200
	ds_read_b64_tr_b16 v[106:107], v194 offset:0xaa00
	ds_read_b64_tr_b16 v[108:109], v194 offset:0xb200
	v_mfma_f32_32x32x16_bf16 v[64:79], v[176:179], v[84:87], v[64:79]
	ds_read_b64_tr_b16 v[110:111], v194 offset:0xba00
	v_mfma_f32_32x32x16_bf16 v[64:79], v[184:187], v[88:91], v[64:79]
	v_mfma_f32_32x32x16_bf16 v[64:79], v[180:183], v[92:95], v[64:79]
	s_waitcnt lgkmcnt(0)
	v_mfma_f32_32x32x16_bf16 v[80:95], v[172:175], v[96:99], v[16:31]
	ds_read_b64_tr_b16 v[112:113], v194 offset:0x8400
	ds_read_b64_tr_b16 v[114:115], v194 offset:0x8c00
	ds_read_b64_tr_b16 v[116:117], v194 offset:0x9400
	ds_read_b64_tr_b16 v[118:119], v194 offset:0x9c00
	ds_read_b64_tr_b16 v[120:121], v194 offset:0xa400
	ds_read_b64_tr_b16 v[122:123], v194 offset:0xac00
	ds_read_b64_tr_b16 v[124:125], v194 offset:0xb400
	v_mfma_f32_32x32x16_bf16 v[80:95], v[176:179], v[100:103], v[80:95]
	ds_read_b64_tr_b16 v[126:127], v194 offset:0xbc00
	s_add_i32 s38, s87, -3
	s_add_i32 s50, s53, 1
	s_and_b64 s[4:5], s[46:47], exec
	s_cselect_b32 s4, s38, s50
	s_lshl_b32 s4, s4, 6
	s_cmp_le_i32 s4, s86
	s_cbranch_scc1 .Lm0_h1A_nm
	v_mov_b32_e32 v128, v204
	v_mov_b32_e32 v129, v204
	v_mov_b32_e32 v130, v204
	v_mov_b32_e32 v131, v204
	v_mov_b32_e32 v132, v204
	v_mov_b32_e32 v133, v204
	v_mov_b32_e32 v134, v204
	v_mov_b32_e32 v135, v204
	v_mov_b32_e32 v136, v204
	v_mov_b32_e32 v137, v204
	v_mov_b32_e32 v138, v204
	v_mov_b32_e32 v139, v204
	v_mov_b32_e32 v140, v204
	v_mov_b32_e32 v141, v204
	v_mov_b32_e32 v142, v204
	v_mov_b32_e32 v143, v204
.Lm0_h1A_nm:
	v_max3_f32 v0, v128, v129, v130
	v_max3_f32 v17, v131, v132, v133
	v_max3_f32 v18, v134, v135, v136
	v_max3_f32 v19, v137, v138, v139
	v_mfma_f32_32x32x16_bf16 v[80:95], v[184:187], v[104:107], v[80:95]
	v_max3_f32 v20, v140, v141, v142
	v_max3_f32 v0, v0, v17, v143
	v_max3_f32 v18, v18, v19, v20
	v_max_f32_e32 v0, v0, v18
	v_mov_b32_e32 v17, v0
	s_nop 1
	v_permlane32_swap_b32_e32 v0, v17
	v_max_f32_e32 v0, v0, v17
	v_mfma_f32_32x32x16_bf16 v[80:95], v[180:183], v[108:111], v[80:95]
	s_waitcnt lgkmcnt(0)
	v_mfma_f32_32x32x16_bf16 v[96:111], v[172:175], v[112:115], v[32:47]
	ds_read_b64_tr_b16 v[230:231], v194 offset:0x8600
	ds_read_b64_tr_b16 v[232:233], v194 offset:0x8e00
	ds_read_b64_tr_b16 v[234:235], v194 offset:0x9600
	ds_read_b64_tr_b16 v[236:237], v194 offset:0x9e00
	ds_read_b64_tr_b16 v[238:239], v194 offset:0xa600
	ds_read_b64_tr_b16 v[240:241], v194 offset:0xae00
	ds_read_b64_tr_b16 v[242:243], v194 offset:0xb600
	s_and_saveexec_b64 s[4:5], s[2:3]
	ds_write_b32 v226, v0
	s_or_b64 exec, exec, s[4:5]
	s_cmp_le_u32 s38, s84
	s_cselect_b64 s[4:5], -1, 0
	s_cmp_gt_u32 s38, s84
	s_cbranch_scc1 .Lm0_h1A_381
	s_waitcnt vmcnt(1)
	ds_write_b128 v215, v[148:151]
	s_waitcnt vmcnt(0)
	ds_write_b128 v215, v[152:155] offset:8192

.Lm0_h1A_385:
	s_waitcnt lgkmcnt(0)
	v_mfma_f32_32x32x16_bf16 v[112:127], v[172:175], v[230:233], v[48:63]
	v_mul_f32_e32 v17, 0xbe0293ee, v218
	v_fmamk_f32 v16, v128, 0x3e0293ee, v17
	v_fmamk_f32 v15, v129, 0x3e0293ee, v17
	v_fmamk_f32 v14, v130, 0x3e0293ee, v17
	v_fmamk_f32 v13, v131, 0x3e0293ee, v17
	v_exp_f32_e32 v16, v16
	v_exp_f32_e32 v15, v15
	v_exp_f32_e32 v14, v14
	v_exp_f32_e32 v13, v13
	v_mfma_f32_32x32x16_bf16 v[112:127], v[176:179], v[234:237], v[112:127]
	v_fmamk_f32 v12, v132, 0x3e0293ee, v17
	v_fmamk_f32 v11, v133, 0x3e0293ee, v17
	v_fmamk_f32 v10, v134, 0x3e0293ee, v17
	v_fmamk_f32 v9, v135, 0x3e0293ee, v17
	v_exp_f32_e32 v12, v12
	v_exp_f32_e32 v11, v11
	v_exp_f32_e32 v10, v10
	v_exp_f32_e32 v9, v9
	v_mfma_f32_32x32x16_bf16 v[112:127], v[184:187], v[238:241], v[112:127]
	v_fmamk_f32 v8, v136, 0x3e0293ee, v17
	v_fmamk_f32 v7, v137, 0x3e0293ee, v17
	v_fmamk_f32 v6, v138, 0x3e0293ee, v17
	v_fmamk_f32 v5, v139, 0x3e0293ee, v17
	v_exp_f32_e32 v8, v8
	v_exp_f32_e32 v7, v7
	v_exp_f32_e32 v6, v6
	v_exp_f32_e32 v5, v5
	v_mfma_f32_32x32x16_bf16 v[112:127], v[180:183], v[242:245], v[112:127]
	v_fmamk_f32 v4, v140, 0x3e0293ee, v17
	v_fmamk_f32 v3, v141, 0x3e0293ee, v17
	v_fmamk_f32 v2, v142, 0x3e0293ee, v17
	v_fmac_f32_e32 v17, 0x3e0293ee, v143
	v_exp_f32_e32 v4, v4
	v_exp_f32_e32 v3, v3
	v_exp_f32_e32 v2, v2
	v_exp_f32_e32 v1, v17
	v_add_f32_e32 v17, v16, v15
	v_add_f32_e32 v18, v14, v13
	v_add_f32_e32 v17, v17, v18
	v_add_f32_e32 v18, v12, v11
	v_add_f32_e32 v19, v10, v9
	v_add_f32_e32 v18, v18, v19
	v_add_f32_e32 v17, v17, v18
	v_add_f32_e32 v18, v8, v7
	v_add_f32_e32 v19, v6, v5
	v_add_f32_e32 v18, v18, v19
	v_add_f32_e32 v19, v4, v3
	v_add_f32_e32 v20, v2, v1
	v_add_f32_e32 v19, v19, v20
	v_add_f32_e32 v18, v18, v19
	v_add_f32_e32 v231, v17, v18
	v_mov_b32_e32 v232, v231
	s_nop 1
	v_permlane32_swap_b32_e32 v231, v232
	v_cvt_pk_bf16_f32 v172, v16, v15
	v_cvt_pk_bf16_f32 v173, v14, v13
	v_cvt_pk_bf16_f32 v174, v12, v11
	v_cvt_pk_bf16_f32 v175, v10, v9
	v_cvt_pk_bf16_f32 v176, v8, v7
	v_cvt_pk_bf16_f32 v177, v6, v5
	v_cvt_pk_bf16_f32 v178, v4, v3
	v_cvt_pk_bf16_f32 v179, v2, v1
	s_nop 0
	v_permlane32_swap_b32_e32 v172, v174
	v_permlane32_swap_b32_e32 v173, v175
	v_permlane32_swap_b32_e32 v176, v178
	v_permlane32_swap_b32_e32 v177, v179
	ds_write_b128 v219, v[172:175]
	ds_write_b128 v219, v[176:179] offset:1024

; template <int KB> __device__ __forceinline__ void qkt_half(f32x16& p, const char* K_lds, int r32, int hi, int kh, const char* qf, bf16x8 q0) {
;     p = f32x16{};
;     const char* kb[4];
; #pragma unroll
;     for (int dd = 0; dd < 4; ++dd) kb[dd] = K_lds + KB * SHM_K + kh * 8192 + KSWZ(r32, (dd * 16 + hi * 8) * 2);
; #pragma unroll
;     for (int d0 = 0; d0 < 8; ++d0) { const bf16x8 b0 = *reinterpret_cast<const bf16x8*>(kb[d0 & 3] + (d0 >> 2) * 128); const bf16x8 q = d0 == 0 ? q0 : *reinterpret_cast<const bf16x8*>(qf + (d0 - 1) * 1024); p = __builtin_amdgcn_mfma_f32_32x32x16_bf16(b0, q, p, 0, 0, 0); }
.LBB0_386:
	ds_read_b128 v[184:187], v220
	ds_read_b128 v[180:183], v220 offset:1024
	ds_read_b128 v[0:3], v222
	ds_read_b128 v[4:7], v222 offset:128
	s_waitcnt lgkmcnt(1)
	v_mfma_f32_32x32x16_bf16 v[128:143], v[0:3], v[144:147], 0
	ds_read_b128 v[0:3], v223
	ds_read_b128 v[8:11], v210
	ds_read_b128 v[12:15], v210 offset:1024
	ds_read_b128 v[16:19], v223 offset:128
	s_waitcnt lgkmcnt(2)
	v_mfma_f32_32x32x16_bf16 v[128:143], v[0:3], v[8:11], v[128:143]
	ds_read_b128 v[0:3], v224
	ds_read_b128 v[8:11], v224 offset:128
	s_waitcnt lgkmcnt(1)
	v_mfma_f32_32x32x16_bf16 v[128:143], v[0:3], v[12:15], v[128:143]
	ds_read_b128 v[0:3], v225
	ds_read_b128 v[12:15], v210 offset:2048
	ds_read_b128 v[20:23], v210 offset:3072
	ds_read_b128 v[24:27], v225 offset:128
	s_waitcnt lgkmcnt(2)
	v_mfma_f32_32x32x16_bf16 v[128:143], v[0:3], v[12:15], v[128:143]
	s_waitcnt lgkmcnt(1)
	v_mfma_f32_32x32x16_bf16 v[128:143], v[4:7], v[20:23], v[128:143]
	ds_read_b128 v[0:3], v210 offset:4096
	ds_read_b128 v[4:7], v210 offset:5120
	s_waitcnt lgkmcnt(1)
	v_mfma_f32_32x32x16_bf16 v[128:143], v[16:19], v[0:3], v[128:143]
	ds_read_b128 v[0:3], v210 offset:6144
	s_waitcnt lgkmcnt(1)
	v_mfma_f32_32x32x16_bf16 v[128:143], v[8:11], v[4:7], v[128:143]
	s_waitcnt lgkmcnt(0)
	v_mfma_f32_32x32x16_bf16 v[128:143], v[24:27], v[0:3], v[128:143]
	s_mov_b64 s[4:5], -1
	s_and_b64 vcc, exec, s[48:49]
	s_cbranch_vccz .LBB0_388
	ds_read_b64_tr_b16 v[16:17], v194 offset:0x4000
	ds_read_b64_tr_b16 v[18:19], v194 offset:0x4800
	ds_read_b64_tr_b16 v[20:21], v194 offset:0x5000
	ds_read_b64_tr_b16 v[22:23], v194 offset:0x5800
	ds_read_b64_tr_b16 v[24:25], v194 offset:0x6000
	ds_read_b64_tr_b16 v[26:27], v194 offset:0x6800
	ds_read_b64_tr_b16 v[28:29], v194 offset:0x7000
	ds_read_b64_tr_b16 v[30:31], v194 offset:0x7800
	s_waitcnt lgkmcnt(0)
	s_nop 0
	v_mfma_f32_32x32x16_bf16 v[0:15], v[184:187], v[16:19], v[64:79]
	ds_read_b64_tr_b16 v[32:33], v194 offset:0x4200
	ds_read_b64_tr_b16 v[34:35], v194 offset:0x4a00
	ds_read_b64_tr_b16 v[36:37], v194 offset:0x5200
	ds_read_b64_tr_b16 v[38:39], v194 offset:0x5a00
	ds_read_b64_tr_b16 v[40:41], v194 offset:0x6200
	ds_read_b64_tr_b16 v[42:43], v194 offset:0x6a00
	ds_read_b64_tr_b16 v[44:45], v194 offset:0x7200
	v_mfma_f32_32x32x16_bf16 v[0:15], v[180:183], v[20:23], v[0:15]
	ds_read_b64_tr_b16 v[46:47], v194 offset:0x7a00
	v_mfma_f32_32x32x16_bf16 v[0:15], v[172:175], v[24:27], v[0:15]
	v_mfma_f32_32x32x16_bf16 v[0:15], v[176:179], v[28:31], v[0:15]
	s_waitcnt lgkmcnt(0)
	v_mfma_f32_32x32x16_bf16 v[16:31], v[184:187], v[32:35], v[80:95]
	ds_read_b64_tr_b16 v[48:49], v194 offset:0x4400
	ds_read_b64_tr_b16 v[50:51], v194 offset:0x4c00
	ds_read_b64_tr_b16 v[52:53], v194 offset:0x5400
	ds_read_b64_tr_b16 v[54:55], v194 offset:0x5c00
	ds_read_b64_tr_b16 v[56:57], v194 offset:0x6400
	ds_read_b64_tr_b16 v[58:59], v194 offset:0x6c00
	ds_read_b64_tr_b16 v[60:61], v194 offset:0x7400
	v_mfma_f32_32x32x16_bf16 v[16:31], v[180:183], v[36:39], v[16:31]
	ds_read_b64_tr_b16 v[62:63], v194 offset:0x7c00
	s_and_b64 s[4:5], s[46:47], exec
	s_cselect_b32 s4, s89, s53
	s_lshl_b32 s4, s4, 6
	s_cmp_le_i32 s4, s86
	s_cbranch_scc1 .Lm0_h2B_nm
	v_mov_b32_e32 v128, v204
	v_mov_b32_e32 v129, v204
	v_mov_b32_e32 v130, v204
	v_mov_b32_e32 v131, v204
	v_mov_b32_e32 v132, v204
	v_mov_b32_e32 v133, v204
	v_mov_b32_e32 v134, v204
	v_mov_b32_e32 v135, v204
	v_mov_b32_e32 v136, v204
	v_mov_b32_e32 v137, v204
	v_mov_b32_e32 v138, v204
	v_mov_b32_e32 v139, v204
	v_mov_b32_e32 v140, v204
	v_mov_b32_e32 v141, v204
	v_mov_b32_e32 v142, v204
	v_mov_b32_e32 v143, v204
.Lm0_h2B_nm:
	v_max3_f32 v64, v128, v129, v130
	v_max3_f32 v81, v131, v132, v133
	v_max3_f32 v82, v134, v135, v136
	v_max3_f32 v83, v137, v138, v139
	v_mfma_f32_32x32x16_bf16 v[16:31], v[172:175], v[40:43], v[16:31]
	v_max3_f32 v84, v140, v141, v142
	v_max3_f32 v64, v64, v81, v143
	v_max3_f32 v82, v82, v83, v84
	v_max_f32_e32 v64, v64, v82
	v_mov_b32_e32 v81, v64
	s_nop 1
	v_permlane32_swap_b32_e32 v64, v81
	v_max_f32_e32 v64, v64, v81
	v_mfma_f32_32x32x16_bf16 v[16:31], v[176:179], v[44:47], v[16:31]
	s_waitcnt lgkmcnt(0)
	v_mfma_f32_32x32x16_bf16 v[32:47], v[184:187], v[48:51], v[96:111]
	ds_read_b64_tr_b16 v[234:235], v194 offset:0x4600
	ds_read_b64_tr_b16 v[236:237], v194 offset:0x4e00
	ds_read_b64_tr_b16 v[238:239], v194 offset:0x5600
	ds_read_b64_tr_b16 v[240:241], v194 offset:0x5e00
	ds_read_b64_tr_b16 v[242:243], v194 offset:0x6600
	ds_read_b64_tr_b16 v[244:245], v194 offset:0x6e00
	ds_read_b64_tr_b16 v[246:247], v194 offset:0x7600
	s_and_saveexec_b64 s[4:5], s[2:3]
	ds_write_b32 v226, v64 offset:1024
	s_or_b64 exec, exec, s[4:5]
	v_cndmask_b32_e64 v81, 0, 1, s[50:51]
	v_cmp_ne_u32_e64 s[4:5], 1, v81
	s_andn2_b64 vcc, exec, s[50:51]
	s_cbranch_vccnz .Lm0_h2B_398
	s_waitcnt vmcnt(1)
	ds_write_b128 v228, v[148:151]
	s_waitcnt vmcnt(0)
	ds_write_b128 v228, v[152:155] offset:8192

.Lm0_h2B_367:
	s_waitcnt lgkmcnt(0)
	v_mfma_f32_32x32x16_bf16 v[48:63], v[184:187], v[234:237], v[112:127]
	v_add_f32_e32 v90, v231, v232
	v_fmac_f32_e32 v90, v227, v229
	v_mul_f32_e32 v89, 0xbe0293ee, v218
	v_fmamk_f32 v80, v128, 0x3e0293ee, v89
	v_fmamk_f32 v79, v129, 0x3e0293ee, v89
	v_fmamk_f32 v78, v130, 0x3e0293ee, v89
	v_fmamk_f32 v77, v131, 0x3e0293ee, v89
	v_fmamk_f32 v72, v136, 0x3e0293ee, v89
	v_fmamk_f32 v71, v137, 0x3e0293ee, v89
	v_fmamk_f32 v70, v138, 0x3e0293ee, v89
	v_fmamk_f32 v69, v139, 0x3e0293ee, v89
	v_exp_f32_e32 v80, v80
	v_exp_f32_e32 v82, v79
	v_exp_f32_e32 v78, v78
	v_exp_f32_e32 v84, v77
	v_mfma_f32_32x32x16_bf16 v[48:63], v[180:183], v[238:241], v[48:63]
	v_fmamk_f32 v76, v132, 0x3e0293ee, v89
	v_fmamk_f32 v75, v133, 0x3e0293ee, v89
	v_fmamk_f32 v74, v134, 0x3e0293ee, v89
	v_fmamk_f32 v73, v135, 0x3e0293ee, v89
	v_exp_f32_e32 v81, v72
	v_exp_f32_e32 v83, v71
	v_exp_f32_e32 v79, v70
	v_exp_f32_e32 v85, v69
	v_mfma_f32_32x32x16_bf16 v[48:63], v[172:175], v[242:245], v[48:63]
	v_fmamk_f32 v68, v140, 0x3e0293ee, v89
	v_fmamk_f32 v67, v141, 0x3e0293ee, v89
	v_fmamk_f32 v66, v142, 0x3e0293ee, v89
	v_fmac_f32_e32 v89, 0x3e0293ee, v143
	v_exp_f32_e32 v76, v76
	v_exp_f32_e32 v86, v75
	v_exp_f32_e32 v74, v74
	v_exp_f32_e32 v88, v73
	v_mfma_f32_32x32x16_bf16 v[48:63], v[176:179], v[246:249], v[48:63]
	v_exp_f32_e32 v77, v68
	v_exp_f32_e32 v87, v67
	v_exp_f32_e32 v75, v66
	v_exp_f32_e32 v89, v89
	v_pk_add_f32 v[66:67], v[80:81], v[82:83]
	v_pk_add_f32 v[68:69], v[78:79], v[84:85]
	v_pk_add_f32 v[70:71], v[74:75], v[88:89]
	v_pk_add_f32 v[66:67], v[66:67], v[68:69]
	v_pk_add_f32 v[68:69], v[76:77], v[86:87]
	s_nop 0
	v_pk_add_f32 v[68:69], v[68:69], v[70:71]
	s_nop 0
	v_pk_add_f32 v[66:67], v[66:67], v[68:69]
	s_nop 0
	v_pk_add_f32 v[66:67], v[66:67], v[66:67] op_sel:[0,1] op_sel_hi:[1,0]
	s_nop 0
	v_mov_b32_e32 v65, v66
	s_nop 1
	v_permlane32_swap_b32_e32 v66, v65
	v_add_f32_e32 v227, v66, v65
	v_fmac_f32_e32 v227, v90, v230
	v_cvt_pk_bf16_f32 v172, v80, v82
	v_cvt_pk_bf16_f32 v173, v78, v84
	v_cvt_pk_bf16_f32 v174, v76, v86
	v_cvt_pk_bf16_f32 v175, v74, v88
	v_cvt_pk_bf16_f32 v176, v81, v83
	v_cvt_pk_bf16_f32 v177, v79, v85
	v_cvt_pk_bf16_f32 v178, v77, v87
	v_cvt_pk_bf16_f32 v179, v75, v89
	s_nop 0
	v_permlane32_swap_b32_e32 v172, v174
	v_permlane32_swap_b32_e32 v173, v175
	v_permlane32_swap_b32_e32 v176, v178
	v_permlane32_swap_b32_e32 v177, v179
	ds_write_b128 v219, v[172:175] offset:16384
	ds_write_b128 v219, v[176:179] offset:17408
	s_mov_b64 s[4:5], 0
.LBB0_388:
	s_andn2_b64 vcc, exec, s[4:5]
	s_cbranch_vccnz .LBB0_390
	ds_read_b64_tr_b16 v[16:17], v194 offset:0
	ds_read_b64_tr_b16 v[18:19], v194 offset:0x800
	ds_read_b64_tr_b16 v[20:21], v194 offset:0x1000
	ds_read_b64_tr_b16 v[22:23], v194 offset:0x1800
	ds_read_b64_tr_b16 v[24:25], v194 offset:0x2000
	ds_read_b64_tr_b16 v[26:27], v194 offset:0x2800
	ds_read_b64_tr_b16 v[28:29], v194 offset:0x3000
	ds_read_b64_tr_b16 v[30:31], v194 offset:0x3800
	s_waitcnt lgkmcnt(0)
	s_nop 0
	v_mfma_f32_32x32x16_bf16 v[0:15], v[172:175], v[16:19], v[64:79]
	ds_read_b64_tr_b16 v[32:33], v194 offset:0x200
	ds_read_b64_tr_b16 v[34:35], v194 offset:0xa00
	ds_read_b64_tr_b16 v[36:37], v194 offset:0x1200
	ds_read_b64_tr_b16 v[38:39], v194 offset:0x1a00
	ds_read_b64_tr_b16 v[40:41], v194 offset:0x2200
	ds_read_b64_tr_b16 v[42:43], v194 offset:0x2a00
	ds_read_b64_tr_b16 v[44:45], v194 offset:0x3200
	v_mfma_f32_32x32x16_bf16 v[0:15], v[176:179], v[20:23], v[0:15]
	ds_read_b64_tr_b16 v[46:47], v194 offset:0x3a00
	v_mfma_f32_32x32x16_bf16 v[0:15], v[184:187], v[24:27], v[0:15]
	v_mfma_f32_32x32x16_bf16 v[0:15], v[180:183], v[28:31], v[0:15]
	s_waitcnt lgkmcnt(0)
	v_mfma_f32_32x32x16_bf16 v[16:31], v[172:175], v[32:35], v[80:95]
	ds_read_b64_tr_b16 v[48:49], v194 offset:0x400
	ds_read_b64_tr_b16 v[50:51], v194 offset:0xc00
	ds_read_b64_tr_b16 v[52:53], v194 offset:0x1400
	ds_read_b64_tr_b16 v[54:55], v194 offset:0x1c00
	ds_read_b64_tr_b16 v[56:57], v194 offset:0x2400
	ds_read_b64_tr_b16 v[58:59], v194 offset:0x2c00
	ds_read_b64_tr_b16 v[60:61], v194 offset:0x3400
	v_mfma_f32_32x32x16_bf16 v[16:31], v[176:179], v[36:39], v[16:31]
	ds_read_b64_tr_b16 v[62:63], v194 offset:0x3c00
	s_and_b64 s[4:5], s[46:47], exec
	s_cselect_b32 s4, s89, s53
	s_lshl_b32 s4, s4, 6
	s_cmp_le_i32 s4, s86
	s_cbranch_scc1 .Lm0_h2A_nm
	v_mov_b32_e32 v128, v204
	v_mov_b32_e32 v129, v204
	v_mov_b32_e32 v130, v204
	v_mov_b32_e32 v131, v204
	v_mov_b32_e32 v132, v204
	v_mov_b32_e32 v133, v204
	v_mov_b32_e32 v134, v204
	v_mov_b32_e32 v135, v204
	v_mov_b32_e32 v136, v204
	v_mov_b32_e32 v137, v204
	v_mov_b32_e32 v138, v204
	v_mov_b32_e32 v139, v204
	v_mov_b32_e32 v140, v204
	v_mov_b32_e32 v141, v204
	v_mov_b32_e32 v142, v204
	v_mov_b32_e32 v143, v204
.Lm0_h2A_nm:
	v_max3_f32 v64, v128, v129, v130
	v_max3_f32 v81, v131, v132, v133
	v_max3_f32 v82, v134, v135, v136
	v_max3_f32 v83, v137, v138, v139
	v_mfma_f32_32x32x16_bf16 v[16:31], v[184:187], v[40:43], v[16:31]
	v_max3_f32 v84, v140, v141, v142
	v_max3_f32 v64, v64, v81, v143
	v_max3_f32 v82, v82, v83, v84
	v_max_f32_e32 v64, v64, v82
	v_mov_b32_e32 v81, v64
	s_nop 1
	v_permlane32_swap_b32_e32 v64, v81
	v_max_f32_e32 v64, v64, v81
	v_mfma_f32_32x32x16_bf16 v[16:31], v[180:183], v[44:47], v[16:31]
	s_waitcnt lgkmcnt(0)
	v_mfma_f32_32x32x16_bf16 v[32:47], v[172:175], v[48:51], v[96:111]
	ds_read_b64_tr_b16 v[234:235], v194 offset:0x600
	ds_read_b64_tr_b16 v[236:237], v194 offset:0xe00
	ds_read_b64_tr_b16 v[238:239], v194 offset:0x1600
	ds_read_b64_tr_b16 v[240:241], v194 offset:0x1e00
	ds_read_b64_tr_b16 v[242:243], v194 offset:0x2600
	ds_read_b64_tr_b16 v[244:245], v194 offset:0x2e00
	ds_read_b64_tr_b16 v[246:247], v194 offset:0x3600
	s_and_saveexec_b64 s[4:5], s[2:3]
	ds_write_b32 v226, v64 offset:1024
	s_or_b64 exec, exec, s[4:5]
	v_cndmask_b32_e64 v81, 0, 1, s[50:51]
	v_cmp_ne_u32_e64 s[4:5], 1, v81
	s_andn2_b64 vcc, exec, s[50:51]
	s_cbranch_vccnz .Lm0_h2A_398
	s_waitcnt vmcnt(1)
	ds_write_b128 v228, v[148:151]
	s_waitcnt vmcnt(0)
	ds_write_b128 v228, v[152:155] offset:8192

.Lm0_h2A_367:
	s_waitcnt lgkmcnt(0)
	v_mfma_f32_32x32x16_bf16 v[48:63], v[172:175], v[234:237], v[112:127]
	v_add_f32_e32 v90, v231, v232
	v_fmac_f32_e32 v90, v227, v229
	v_mul_f32_e32 v89, 0xbe0293ee, v218
	v_fmamk_f32 v80, v128, 0x3e0293ee, v89
	v_fmamk_f32 v79, v129, 0x3e0293ee, v89
	v_fmamk_f32 v78, v130, 0x3e0293ee, v89
	v_fmamk_f32 v77, v131, 0x3e0293ee, v89
	v_fmamk_f32 v72, v136, 0x3e0293ee, v89
	v_fmamk_f32 v71, v137, 0x3e0293ee, v89
	v_fmamk_f32 v70, v138, 0x3e0293ee, v89
	v_fmamk_f32 v69, v139, 0x3e0293ee, v89
	v_exp_f32_e32 v80, v80
	v_exp_f32_e32 v82, v79
	v_exp_f32_e32 v78, v78
	v_exp_f32_e32 v84, v77
	v_mfma_f32_32x32x16_bf16 v[48:63], v[176:179], v[238:241], v[48:63]
	v_fmamk_f32 v76, v132, 0x3e0293ee, v89
	v_fmamk_f32 v75, v133, 0x3e0293ee, v89
	v_fmamk_f32 v74, v134, 0x3e0293ee, v89
	v_fmamk_f32 v73, v135, 0x3e0293ee, v89
	v_exp_f32_e32 v81, v72
	v_exp_f32_e32 v83, v71
	v_exp_f32_e32 v79, v70
	v_exp_f32_e32 v85, v69
	v_mfma_f32_32x32x16_bf16 v[48:63], v[184:187], v[242:245], v[48:63]
	v_fmamk_f32 v68, v140, 0x3e0293ee, v89
	v_fmamk_f32 v67, v141, 0x3e0293ee, v89
	v_fmamk_f32 v66, v142, 0x3e0293ee, v89
	v_fmac_f32_e32 v89, 0x3e0293ee, v143
	v_exp_f32_e32 v76, v76
	v_exp_f32_e32 v86, v75
	v_exp_f32_e32 v74, v74
	v_exp_f32_e32 v88, v73
	v_mfma_f32_32x32x16_bf16 v[48:63], v[180:183], v[246:249], v[48:63]
	v_exp_f32_e32 v77, v68
	v_exp_f32_e32 v87, v67
	v_exp_f32_e32 v75, v66
	v_exp_f32_e32 v89, v89
	v_pk_add_f32 v[66:67], v[80:81], v[82:83]
	v_pk_add_f32 v[68:69], v[78:79], v[84:85]
	v_pk_add_f32 v[70:71], v[74:75], v[88:89]
	v_pk_add_f32 v[66:67], v[66:67], v[68:69]
	v_pk_add_f32 v[68:69], v[76:77], v[86:87]
	s_nop 0
	v_pk_add_f32 v[68:69], v[68:69], v[70:71]
	s_nop 0
	v_pk_add_f32 v[66:67], v[66:67], v[68:69]
	s_nop 0
	v_pk_add_f32 v[66:67], v[66:67], v[66:67] op_sel:[0,1] op_sel_hi:[1,0]
	s_nop 0
	v_mov_b32_e32 v65, v66
	s_nop 1
	v_permlane32_swap_b32_e32 v66, v65
	v_add_f32_e32 v227, v66, v65
	v_fmac_f32_e32 v227, v90, v230
	v_cvt_pk_bf16_f32 v172, v80, v82
	v_cvt_pk_bf16_f32 v173, v78, v84
	v_cvt_pk_bf16_f32 v174, v76, v86
	v_cvt_pk_bf16_f32 v175, v74, v88
	v_cvt_pk_bf16_f32 v176, v81, v83
	v_cvt_pk_bf16_f32 v177, v79, v85
	v_cvt_pk_bf16_f32 v178, v77, v87
	v_cvt_pk_bf16_f32 v179, v75, v89
	s_nop 0
	v_permlane32_swap_b32_e32 v172, v174
	v_permlane32_swap_b32_e32 v173, v175
	v_permlane32_swap_b32_e32 v176, v178
	v_permlane32_swap_b32_e32 v177, v179
	ds_write_b128 v219, v[172:175] offset:16384
	ds_write_b128 v219, v[176:179] offset:17408
